# P6: WGs with blockIdx bit3 run skinny0 before UpA/UpB GEMMs so the read-bound GEMM epilogues of the two halves interleave
# speedup vs baseline: 1.0018x; 1.0018x over previous
; template <class Epi>
; __device__ __forceinline__ void gemm_phase(LAS unsigned char* lds, const Gemm g, const StaticOrder& S, const Epi& E) {
;     const int tid = threadIdx.x, wid = __builtin_amdgcn_readfirstlane(tid >> 6), lane = tid & 63, wr = wid >> 2, wc = wid & 3, fr = lane & 15, fq = lane >> 4;
;     const int K = g.K, nt = K / BK;
;     unsigned voffA[2], voffB[2];
; #pragma unroll
;     for (int i = 0; i < 2; ++i) { int R, C; stage_rc(tid * 16 + i * 8192, R, C); const int Rb = Epi::PERM ? ((R & ~31) + perm32(R & 31)) : R;
;         voffA[i] = (unsigned)(R * K + C) * 2u; voffB[i] = (unsigned)(Rb * K + C) * 2u; }
;     const size_t kstep = (size_t)(BK * 2);
;     const size_t hstep = (size_t)HALF * K * 2;
;     const size_t tstep = 2 * hstep;
;     const unsigned ldsw = (unsigned)wid * 1024u;
;     const int aoff = lds_byte(wr * 64 + fr, fq * 8), boff = lds_byte(wc * 32 + fr, fq * 8);
;     ...
;     Unit cur, nxt; int ui = 0;
;     if (!S.next(0, cur)) return;
;     f32x4 acc[2][2][4][2];
; #pragma unroll
;     for (int a = 0; a < 2; ++a)
; #pragma unroll
;         for (int b = 0; b < 2; ++b)
; #pragma unroll
;             for (int m = 0; m < 4; ++m)
; #pragma unroll
;                 for (int n = 0; n < 2; ++n) acc[a][b][m][n] = (f32x4){0.f, 0.f, 0.f, 0.f};
;     bf16x8 At[4][2], B0[2][2], B1[2][2];
;     const char* cA = (const char*)g.A + (size_t)cur.pm * tstep; const char* cB = (const char*)g.Bt + (size_t)cur.pn * tstep;
;     PG8_STAGE(PG8_SB(0, 0), cB, voffB); PG8_STAGE(PG8_SA(0, 0), cA, voffA); PG8_STAGE(PG8_SB(0, 1), cB + hstep, voffB); PG8_STAGE(PG8_SA(0, 1), cA + hstep, voffA);
;     if (wr == 1) PG8_BAR;
;     PG8_WAIT_V(4); PG8_BAR;
; __global__ void __launch_bounds__(512, 2) fwd(Params P) {
;     ...
;     if (IN(6)) for (int rep_ = 0; rep_ < NREP(6); ++rep_) { pg8::StaticOrder S; S.init(ROW_S, D, gridDim.x, blockIdx.x);
;         { pg8::Gemm g{(const bf16_t*)(ws + O_YA), (const bf16_t*)(ws + O_WAT), ROW_S, D, 1024}; EpiUpA E{(const bf16_t*)(ws + O_PROJ), (bf16_t*)(ws + O_TMP)}; pg8::gemm_phase<EpiUpA>((LAS unsigned char*)shm, g, S, E); }
;         { pg8::Gemm g{(const bf16_t*)(ws + O_YB), (const bf16_t*)(ws + O_WBT), ROW_S, D, 1024}; EpiUpB E{(const bf16_t*)(ws + O_PROJ), (const bf16_t*)(ws + O_TMP), (bf16_t*)(ws + O_MIX)}; pg8::gemm_phase<EpiUpB>((LAS unsigned char*)shm, g, S, E); }
;         skinny_phase<0>(P, shm);
.LBB0_902:
	s_cmp_lt_i32 s14, 7
	s_cselect_b64 s[0:1], -1, 0
	s_cmp_gt_i32 s15, 6
	s_cselect_b64 s[2:3], -1, 0
	s_and_b64 s[0:1], s[0:1], s[2:3]
	s_andn2_b64 vcc, exec, s[0:1]
	s_cbranch_vccnz .LBB0_990
	s_bitcmp0_b32 s94, 3
	s_cbranch_scc1 .Lp6_gemm
	v_and_b32_e32 v202, 15, v214
	s_add_u32 s0, s12, 0x4542000
	s_addc_u32 s1, s13, 0
	s_add_u32 s6, s12, 0x18042000
	s_addc_u32 s7, s13, 0
	v_lshlrev_b32_e32 v203, 2, v202
	s_branch .Lsk0_entry
.Lp6_gemm:
	v_lshrrev_b32_e32 v2, 5, v214
	v_lshrrev_b32_e32 v4, 1, v214
	s_add_u32 s0, s12, 0x4542000
	v_and_b32_e32 v2, 4, v2
	v_bfe_u32 v3, v214, 2, 2
	v_and_b32_e32 v180, 24, v4
	s_addc_u32 s1, s13, 0
	v_lshlrev_b32_e32 v0, 4, v214
	v_and_b32_e32 v1, 32, v214
	v_bfe_u32 v170, v214, 2, 4
	v_or3_b32 v2, v2, v3, v180
	v_lshrrev_b32_e32 v3, 3, v214
	s_movk_i32 s2, 0x70
	s_add_u32 s4, s12, 0x13e42000
	v_bitop3_b32 v168, v0, v1, 48 bitop3:0x6c
	v_and_b32_e32 v169, 64, v214
	v_and_or_b32 v4, v3, s2, v170
	s_movk_i32 s2, 0x60
	v_add_u32_e32 v171, 0x2000, v0
	s_addc_u32 s5, s13, 0
	v_or_b32_e32 v1, v168, v169
	v_and_or_b32 v3, v3, s2, v2
	v_lshrrev_b32_e32 v0, 7, v171
	s_movk_i32 s2, 0xf0
	s_ashr_i32 s33, s94, 31
	v_lshl_or_b32 v174, v3, 11, v1
	v_and_or_b32 v3, v0, s2, v170
	s_movk_i32 s2, 0xe0
	s_cmpk_lt_i32 s94, 0x100
	v_and_or_b32 v0, v0, s2, v2
	s_cselect_b64 s[6:7], -1, 0
	s_lshr_b32 s2, s33, 24
	s_add_i32 s2, s94, s2
	s_and_b32 s2, s2, 0xff00
	s_sub_i32 s2, s94, s2
	s_sext_i32_i16 s3, s2
	s_bfe_u32 s3, s3, 0x3001c
	s_add_i32 s3, s2, s3
	s_sext_i32_i16 s8, s3
	s_and_b32 s3, s3, 0xfff8
	s_sub_i32 s47, s2, s3
	s_ashr_i32 s40, s96, 31
	s_lshr_b32 s45, s8, 3
	s_sext_i32_i16 s2, s47
	v_lshl_or_b32 v172, v4, 11, v1
	v_lshl_or_b32 v176, v3, 11, v1
	v_lshl_or_b32 v178, v0, 11, v1
	v_lshlrev_b32_e32 v0, 6, v214
	v_lshlrev_b32_e32 v1, 2, v214
	s_cmp_lt_i32 s2, 0
	v_lshlrev_b32_e32 v181, 1, v180
	v_and_b32_e32 v0, 0x3c0, v0
	v_and_b32_e32 v1, 32, v1
	s_cselect_b64 s[8:9], -1, 0
	s_lshl_b32 s46, s47, 5
	v_mov_b32_e32 v175, 0
	v_and_b32_e32 v202, 15, v214
	v_bitop3_b32 v182, v181, v1, v0 bitop3:0x36
	s_cmpk_gt_i32 s94, 0xff
	v_mov_b32_e32 v179, v175
	v_mov_b32_e32 v173, v175
	v_mov_b32_e32 v177, v175
	s_mul_i32 s47, s47, 33
	v_readfirstlane_b32 s41, v214
	s_cbranch_scc1 .LBB0_919
	s_add_u32 s42, s12, 0x3180000
	s_addc_u32 s43, s13, 0
	s_add_u32 s44, s12, 0xdbc2000
	s_addc_u32 s48, s13, 0
	s_lshr_b32 s10, s41, 6
	s_lshr_b32 s3, s41, 8
	s_lshl_b32 s49, s10, 10
	s_and_b64 s[16:17], s[8:9], exec
	s_cselect_b32 s2, s47, s46
	s_add_i32 s2, s2, s45
	s_sext_i32_i16 s11, s2
	s_bfe_u32 s11, s11, 0x60019
	s_add_i32 s11, s2, s11
	s_sext_i32_i16 s16, s11
	s_and_b32 s11, s11, 0xffc0
	s_sub_i32 s11, s2, s11
	s_bfe_i32 s2, s11, 0x80000
	s_bfe_u32 s2, s2, 0x3000c
	s_add_i32 s17, s11, s2
	s_bfe_i32 s2, s17, 0x80000
	s_and_b32 s17, s17, 0xf8
	s_ashr_i32 s16, s16, 6
	s_sub_i32 s11, s11, s17
	s_lshl_b32 s16, s16, 3
	s_sext_i32_i16 s2, s2
	s_sext_i32_i8 s11, s11
	s_lshr_b32 s2, s2, 3
	s_add_i32 s26, s16, s11
	s_ashr_i32 s27, s26, 31
	s_bfe_i64 s[18:19], s[2:3], 0x100000
	s_lshl_b64 s[16:17], s[26:27], 19
	s_lshl_b64 s[18:19], s[18:19], 19
	s_add_u32 s30, s44, s18
	s_addc_u32 s31, s48, s19
	s_add_i32 s27, s49, 0
	s_add_i32 m0, s27, 0x10000
	v_lshl_add_u64 v[0:1], s[30:31], 0, v[174:175]
	global_load_lds_dwordx4 v[0:1], off
	s_add_i32 m0, s27, 0x12000
	s_add_u32 s28, s42, s16
	v_lshl_add_u64 v[2:3], s[30:31], 0, v[178:179]
	s_addc_u32 s29, s43, s17
	s_add_i32 s50, s27, 0x2000
	global_load_lds_dwordx4 v[2:3], off
	v_lshl_add_u64 v[6:7], s[28:29], 0, v[172:173]
	s_mov_b32 m0, s27
	s_add_u32 s16, s30, 0x40000
	global_load_lds_dwordx4 v[6:7], off
	v_lshl_add_u64 v[4:5], s[28:29], 0, v[176:177]
	s_mov_b32 m0, s50
	s_addc_u32 s17, s31, 0
	global_load_lds_dwordx4 v[4:5], off
	s_add_i32 m0, s27, 0x14000
	v_lshl_add_u64 v[8:9], s[16:17], 0, v[174:175]
	global_load_lds_dwordx4 v[8:9], off
	s_add_i32 m0, s27, 0x16000
	v_lshl_add_u64 v[8:9], s[16:17], 0, v[178:179]
	s_add_u32 s16, s28, 0x40000
	s_addc_u32 s17, s29, 0
	s_add_i32 s51, s27, 0x4000
	global_load_lds_dwordx4 v[8:9], off
	v_lshl_add_u64 v[8:9], s[16:17], 0, v[172:173]
	s_mov_b32 m0, s51
	s_add_i32 s54, s27, 0x6000
	global_load_lds_dwordx4 v[8:9], off
	v_lshl_add_u64 v[8:9], s[16:17], 0, v[176:177]
	s_mov_b32 m0, s54
	s_cmp_lg_u32 s3, 1
	global_load_lds_dwordx4 v[8:9], off
	s_cbranch_scc1 .LBB0_906
	s_barrier

; #define LAS __attribute__((address_space(3)))
; __global__ void __launch_bounds__(512, 2) fwd(Params P) {
;     ...
;         { pg8::Gemm g{(const bf16_t*)(ws + O_YA), (const bf16_t*)(ws + O_WAT), ROW_S, D, 1024}; EpiUpA E{(const bf16_t*)(ws + O_PROJ), (bf16_t*)(ws + O_TMP)}; pg8::gemm_phase<EpiUpA>((LAS unsigned char*)shm, g, S, E); }
;         { pg8::Gemm g{(const bf16_t*)(ws + O_YB), (const bf16_t*)(ws + O_WBT), ROW_S, D, 1024}; EpiUpB E{(const bf16_t*)(ws + O_PROJ), (const bf16_t*)(ws + O_TMP), (bf16_t*)(ws + O_MIX)}; pg8::gemm_phase<EpiUpB>((LAS unsigned char*)shm, g, S, E); }
;         skinny_phase<0>(P, shm);
.LBB0_934:
	s_bitcmp1_b32 s94, 3
	s_cbranch_scc1 .LBB0_936

; __device__ __forceinline__ f32x4 mfma16(bf16x8 a, bf16x8 b, f32x4 c) { return __builtin_amdgcn_mfma_f32_16x16x32_bf16(a, b, c, 0, 0, 0); }
; #define MFMA_SETTLE() do { __builtin_amdgcn_sched_barrier(0); asm volatile("s_nop 15\n\ts_nop 15" ::: "memory"); __builtin_amdgcn_sched_barrier(0); } while (0)
; template <int MODE>
; __device__ __forceinline__ void skinny_phase(const Params& P, unsigned char* shm) {
;     ...
;         const bf16_t* ap = A + (size_t)(ROW_S + 32 * mt + l16) * ld + k0 + 8 * q; const bf16_t* bp = Bt + (size_t)(32 * nt + l16) * ld + k0 + 8 * q;
;         f32x4 acc[2][2];
; #pragma unroll
;         for (int i = 0; i < 2; ++i) { acc[i][0] = (f32x4){0.f, 0.f, 0.f, 0.f}; acc[i][1] = (f32x4){0.f, 0.f, 0.f, 0.f}; }
; #pragma unroll 8
;         for (int ks = 0; ks < nks; ++ks) { const bf16x8 a0 = *(const bf16x8*)(ap + 32 * ks), a1 = *(const bf16x8*)(ap + (size_t)16 * ld + 32 * ks), b0 = *(const bf16x8*)(bp + 32 * ks), b1 = *(const bf16x8*)(bp + (size_t)16 * ld + 32 * ks);
;             acc[0][0] = mfma16(a0, b0, acc[0][0]); acc[0][1] = mfma16(a0, b1, acc[0][1]); acc[1][0] = mfma16(a1, b0, acc[1][0]); acc[1][1] = mfma16(a1, b1, acc[1][1]); }
;         MFMA_SETTLE();
; #pragma unroll
;         for (int mi = 0; mi < 2; ++mi)
; #pragma unroll
;             for (int ni = 0; ni < 2; ++ni)
; #pragma unroll
;                 for (int r = 0; r < 4; ++r) red[wave * 1024 + (16 * mi + 4 * q + r) * 32 + 16 * ni + l16] = acc[mi][ni][r];
.LBB0_935:
	s_and_b32 s0, s4, 0x60
	s_or_b32 s17, s0, 0x2000
	v_or_b32_e32 v0, s17, v202
	v_lshlrev_b32_e32 v0, 11, v0
	s_and_b32 s18, s2, 0xffffffe0
	v_lshl_add_u64 v[58:59], v[2:3], 0, v[0:1]
	v_or_b32_e32 v18, s18, v202
	v_ashrrev_i32_e32 v19, 31, v18
	v_lshlrev_b64 v[18:19], 11, v[18:19]
	v_lshl_add_u64 v[60:61], v[4:5], 0, v[18:19]
	v_add_co_u32_e32 v62, vcc, s9, v58
	s_nop 1
	v_addc_co_u32_e32 v63, vcc, 0, v59, vcc
	v_add_co_u32_e32 v64, vcc, s9, v60
	s_nop 1
	v_addc_co_u32_e32 v65, vcc, 0, v61, vcc
	global_load_dwordx4 v[66:69], v[58:59], off
	global_load_dwordx4 v[70:73], v[60:61], off
	global_load_dwordx4 v[74:77], v[62:63], off
	global_load_dwordx4 v[78:81], v[64:65], off
	global_load_dwordx4 v[82:85], v[58:59], off offset:64
	global_load_dwordx4 v[86:89], v[60:61], off offset:64
	global_load_dwordx4 v[90:93], v[62:63], off offset:64
	global_load_dwordx4 v[94:97], v[64:65], off offset:64
	global_load_dwordx4 v[98:101], v[58:59], off offset:128
	global_load_dwordx4 v[102:105], v[60:61], off offset:128
	global_load_dwordx4 v[106:109], v[62:63], off offset:128
	global_load_dwordx4 v[110:113], v[64:65], off offset:128
	global_load_dwordx4 v[114:117], v[58:59], off offset:192
	global_load_dwordx4 v[118:121], v[60:61], off offset:192
	global_load_dwordx4 v[122:125], v[62:63], off offset:192
	global_load_dwordx4 v[128:131], v[64:65], off offset:192
	global_load_dwordx4 v[132:135], v[58:59], off offset:256
	global_load_dwordx4 v[136:139], v[60:61], off offset:256
	global_load_dwordx4 v[140:143], v[62:63], off offset:256
	global_load_dwordx4 v[144:147], v[64:65], off offset:256
	global_load_dwordx4 v[148:151], v[58:59], off offset:320
	global_load_dwordx4 v[152:155], v[60:61], off offset:320
	global_load_dwordx4 v[156:159], v[62:63], off offset:320
	global_load_dwordx4 v[160:163], v[64:65], off offset:320
	global_load_dwordx4 v[164:167], v[58:59], off offset:384
	global_load_dwordx4 v[168:171], v[60:61], off offset:384
	global_load_dwordx4 v[188:191], v[62:63], off offset:384
	global_load_dwordx4 v[192:195], v[64:65], off offset:384
	global_load_dwordx4 v[196:199], v[58:59], off offset:448
	global_load_dwordx4 v[30:33], v[60:61], off offset:448
	global_load_dwordx4 v[34:37], v[62:63], off offset:448
	global_load_dwordx4 v[38:41], v[64:65], off offset:448
	s_waitcnt vmcnt(28)
	v_mfma_f32_16x16x32_bf16 v[26:29], v[66:69], v[70:73], 0
	v_mfma_f32_16x16x32_bf16 v[14:17], v[66:69], v[78:81], 0
	v_mfma_f32_16x16x32_bf16 v[18:21], v[74:77], v[70:73], 0
	v_mfma_f32_16x16x32_bf16 v[22:25], v[74:77], v[78:81], 0
	s_waitcnt vmcnt(24)
	v_mfma_f32_16x16x32_bf16 v[26:29], v[82:85], v[86:89], v[26:29]
	v_mfma_f32_16x16x32_bf16 v[14:17], v[82:85], v[94:97], v[14:17]
	v_mfma_f32_16x16x32_bf16 v[18:21], v[90:93], v[86:89], v[18:21]
	v_mfma_f32_16x16x32_bf16 v[22:25], v[90:93], v[94:97], v[22:25]
	s_waitcnt vmcnt(20)
	v_mfma_f32_16x16x32_bf16 v[26:29], v[98:101], v[102:105], v[26:29]
	v_mfma_f32_16x16x32_bf16 v[14:17], v[98:101], v[110:113], v[14:17]
	v_mfma_f32_16x16x32_bf16 v[18:21], v[106:109], v[102:105], v[18:21]
	v_mfma_f32_16x16x32_bf16 v[22:25], v[106:109], v[110:113], v[22:25]
	s_waitcnt vmcnt(16)
	v_mfma_f32_16x16x32_bf16 v[26:29], v[114:117], v[118:121], v[26:29]
	v_mfma_f32_16x16x32_bf16 v[14:17], v[114:117], v[128:131], v[14:17]
	v_mfma_f32_16x16x32_bf16 v[18:21], v[122:125], v[118:121], v[18:21]
	v_mfma_f32_16x16x32_bf16 v[22:25], v[122:125], v[128:131], v[22:25]
	s_waitcnt vmcnt(12)
	v_mfma_f32_16x16x32_bf16 v[26:29], v[132:135], v[136:139], v[26:29]
	v_mfma_f32_16x16x32_bf16 v[14:17], v[132:135], v[144:147], v[14:17]
	v_mfma_f32_16x16x32_bf16 v[18:21], v[140:143], v[136:139], v[18:21]
	v_mfma_f32_16x16x32_bf16 v[22:25], v[140:143], v[144:147], v[22:25]
	s_waitcnt vmcnt(8)
	v_mfma_f32_16x16x32_bf16 v[26:29], v[148:151], v[152:155], v[26:29]
	v_mfma_f32_16x16x32_bf16 v[14:17], v[148:151], v[160:163], v[14:17]
	v_mfma_f32_16x16x32_bf16 v[18:21], v[156:159], v[152:155], v[18:21]
	v_mfma_f32_16x16x32_bf16 v[22:25], v[156:159], v[160:163], v[22:25]
	s_waitcnt vmcnt(4)
	v_mfma_f32_16x16x32_bf16 v[26:29], v[164:167], v[168:171], v[26:29]
	v_mfma_f32_16x16x32_bf16 v[14:17], v[164:167], v[192:195], v[14:17]
	v_mfma_f32_16x16x32_bf16 v[18:21], v[188:191], v[168:171], v[18:21]
	v_mfma_f32_16x16x32_bf16 v[22:25], v[188:191], v[192:195], v[22:25]
	s_waitcnt vmcnt(0)
	v_mfma_f32_16x16x32_bf16 v[26:29], v[196:199], v[30:33], v[26:29]
	v_mfma_f32_16x16x32_bf16 v[14:17], v[196:199], v[38:41], v[14:17]
	v_mfma_f32_16x16x32_bf16 v[18:21], v[34:37], v[30:33], v[18:21]
	v_mfma_f32_16x16x32_bf16 v[22:25], v[34:37], v[38:41], v[22:25]
	s_nop 15
	s_nop 15
	s_nop 4
	ds_write2_b32 v11, v26, v14 offset1:16
	ds_write2_b32 v11, v27, v15 offset0:32 offset1:48
	ds_write2_b32 v11, v28, v16 offset0:64 offset1:80
	ds_write2_b32 v11, v29, v17 offset0:96 offset1:112
	ds_write2_b32 v12, v18, v22 offset1:16
	ds_write2_b32 v12, v19, v23 offset0:32 offset1:48
	ds_write2_b32 v12, v20, v24 offset0:64 offset1:80
	ds_write2_b32 v12, v21, v25 offset0:96 offset1:112
	v_or_b32_e32 v14, s18, v9
	v_add_u32_e32 v0, s17, v8
	v_ashrrev_i32_e32 v15, 31, v14
	v_mad_u64_u32 v[16:17], s[0:1], v0, s10, v[6:7]
	v_lshlrev_b64 v[30:31], 1, v[14:15]
	v_lshl_add_u64 v[14:15], v[16:17], 0, v[30:31]
	v_add_co_u32_e32 v16, vcc, s8, v14
	s_waitcnt lgkmcnt(0)
	s_nop 0
	v_addc_co_u32_e32 v17, vcc, 0, v15, vcc
	v_add_co_u32_e32 v14, vcc, s11, v14
	s_barrier
; __device__ __forceinline__ unsigned cvt_pk_bf16(float lo, float hi) { unsigned r; asm volatile("v_cvt_pk_bf16_f32 %0, %1, %2" : "=v"(r) : "v"(lo), "v"(hi)); return r; }
; __device__ __forceinline__ float bflo(unsigned w) { return __uint_as_float(w << 16); }
; __device__ __forceinline__ float bfhi(unsigned w) { return __uint_as_float(w & 0xffff0000u); }
; __device__ __forceinline__ float sigmoidf_(float x) { return __builtin_amdgcn_rcpf(1.0f + __expf(-x)); }
; template <int MODE>
; __device__ __forceinline__ void skinny_phase(const Params& P, unsigned char* shm) {
;     ...
;         __syncthreads();
;         { const int e = tid * 2, rr = e >> 5, cc = e & 31; const int row = ROW_S + 32 * mt + rr, col = 32 * nt + cc;
;           float s0 = 0.f, s1 = 0.f, u0 = 0.f, u1 = 0.f;
; #pragma unroll
;           for (int w = 0; w < 4; ++w) { const f32x2 x = *(const f32x2*)(red + w * 1024 + e), y = *(const f32x2*)(red + (4 + w) * 1024 + e); s0 += x.x; s1 += x.y; u0 += y.x; u1 += y.y; }
;           if (MODE == 0) { const bf16_t* gp = (const bf16_t*)(ws + O_PROJ) + (size_t)row * NPROJ + col;
;               const unsigned ga = *(const unsigned*)(gp + C_GA), gb = *(const unsigned*)(gp + C_GB);
;               const float m0 = sigmoidf_(bflo(ga)) * s0 + sigmoidf_(bflo(gb)) * u0, m1 = sigmoidf_(bfhi(ga)) * s1 + sigmoidf_(bfhi(gb)) * u1;
;               *(unsigned*)((bf16_t*)(ws + O_MIX) + (size_t)row * D + col) = cvt_pk_bf16(m0, m1); }
;           else if (MODE == 1) { const f32x2 xv = *(const f32x2*)(P.in[1] + (size_t)(row - ROW_S) * D + col);
;               *(unsigned*)((bf16_t*)(ws + O_R) + (size_t)row * D + col) = cvt_pk_bf16(ALPHA * xv.x + s0 + u0, ALPHA * xv.y + s1 + u1); }
;           else { const unsigned xw = *(const unsigned*)((const bf16_t*)(ws + O_X1B) + (size_t)row * D + col);
;               *(unsigned*)((bf16_t*)(ws + O_R) + (size_t)row * D + col) = cvt_pk_bf16(ALPHA * bflo(xw) + s0 + u0, ALPHA * bfhi(xw) + s1 + u1); } }
;         __syncthreads();
;     }
	s_nop 0
	v_addc_co_u32_e32 v15, vcc, 0, v15, vcc
	global_load_dword v13, v[16:17], off offset:2048
	global_load_dword v40, v[14:15], off offset:2048
	ds_read2st64_b64 v[14:17], v10 offset1:8
	ds_read2st64_b64 v[18:21], v10 offset0:32 offset1:40
	ds_read2st64_b64 v[22:25], v10 offset0:16 offset1:24
	ds_read2st64_b64 v[26:29], v10 offset0:48 offset1:56
	v_lshlrev_b64 v[32:33], 12, v[0:1]
	v_lshl_add_u64 v[32:33], s[6:7], 0, v[32:33]
	v_lshl_add_u64 v[30:31], v[32:33], 0, v[30:31]
	s_waitcnt lgkmcnt(2)
	v_mov_b32_e32 v33, v18
	v_mov_b32_e32 v18, v15
	v_mov_b32_e32 v34, v16
	v_mov_b32_e32 v35, v20
	v_mov_b32_e32 v20, v17
	v_pk_add_f32 v[16:17], v[18:19], 0 op_sel_hi:[1,0]
	v_mov_b32_e32 v32, v14
	v_pk_add_f32 v[16:17], v[16:17], v[20:21]
	v_pk_add_f32 v[14:15], v[32:33], 0 op_sel_hi:[1,0]
	s_waitcnt lgkmcnt(1)
	v_mov_b32_e32 v36, v22
	s_waitcnt lgkmcnt(0)
	v_mov_b32_e32 v37, v26
	v_pk_add_f32 v[14:15], v[14:15], v[34:35]
	v_mov_b32_e32 v38, v24
	v_mov_b32_e32 v39, v28
	v_mov_b32_e32 v26, v23
	v_pk_add_f32 v[14:15], v[14:15], v[36:37]
	v_mov_b32_e32 v28, v25
	v_pk_add_f32 v[16:17], v[16:17], v[26:27]
	v_pk_add_f32 v[14:15], v[14:15], v[38:39]
	s_add_i32 s16, s16, s96
	s_add_i32 s2, s2, s3
	s_add_i32 s4, s4, s5
	v_pk_add_f32 v[16:17], v[16:17], v[28:29]
	s_cmpk_lt_i32 s16, 0x100
	s_waitcnt vmcnt(1)
	v_lshlrev_b32_e32 v0, 16, v13
	s_waitcnt vmcnt(0)
	v_lshlrev_b32_e32 v18, 16, v40
	v_and_b32_e32 v13, 0xffff0000, v13
	v_and_b32_e32 v19, 0xffff0000, v40
	v_mul_f32_e32 v0, 0xbfb8aa3b, v0
	v_mul_f32_e32 v18, 0xbfb8aa3b, v18
	v_mul_f32_e32 v13, 0xbfb8aa3b, v13
	v_mul_f32_e32 v19, 0xbfb8aa3b, v19
	v_exp_f32_e32 v0, v0
	v_exp_f32_e32 v18, v18
	v_exp_f32_e32 v13, v13
	v_exp_f32_e32 v19, v19
	v_add_f32_e32 v0, 1.0, v0
	v_add_f32_e32 v20, 1.0, v18
	v_add_f32_e32 v13, 1.0, v13
	v_add_f32_e32 v21, 1.0, v19
	v_rcp_f32_e32 v18, v0
	v_rcp_f32_e32 v19, v20
	v_rcp_f32_e32 v20, v13
	v_rcp_f32_e32 v21, v21
	v_pk_mul_f32 v[14:15], v[14:15], v[18:19]
	s_nop 0
	v_add_f32_e32 v0, v14, v15
	v_pk_mul_f32 v[16:17], v[16:17], v[20:21]
	s_nop 0
	v_add_f32_e32 v13, v16, v17
	v_cvt_pk_bf16_f32 v0, v0, v13
	global_store_dword v[30:31], v0, off
	s_barrier
	s_cbranch_scc1 .LBB0_935
	s_bitcmp0_b32 s94, 3
	s_cbranch_scc1 .LBB0_936
	s_branch .Lp6_gemm
